# v8 + non-temporal hint on the read-once f32 x loads in the prologue
# speedup vs baseline: 1.0118x; 1.0118x over previous
; __device__ __forceinline__ unsigned cvt_pk_bf16(float lo, float hi) { unsigned r; asm volatile("v_cvt_pk_bf16_f32 %0, %1, %2" : "=v"(r) : "v"(lo), "v"(hi)); return r; }
; __device__ __forceinline__ void phase0(const Params& p) {
;     ...
;     const int lane = threadIdx.x & 63; const int gw = (int)(gtid >> 6), nw = (int)(gsz >> 6);
;     bf16_t* xb = (bf16_t*)(ws + WS_XB); float* rstd = (float*)(ws + WS_RSTD0);
; #pragma unroll 4
;     for (int row = gw; row < T; row += nw) {
;         const float* xr = (row < T_P) ? p.in[0] + (size_t)row * 1024 : p.in[1] + (size_t)(row - T_P) * 1024;
;         float ss = 0.f;
; #pragma unroll
;         for (int i = 0; i < 4; ++i) {
;             const f32x4 v = *(const f32x4*)(xr + i * 256 + lane * 4);
;             ss += v[0] * v[0] + v[1] * v[1] + v[2] * v[2] + v[3] * v[3];
;             u32x2 w; w.x = cvt_pk_bf16(v[0], v[1]); w.y = cvt_pk_bf16(v[2], v[3]);
;             *(u32x2*)(xb + (size_t)row * 1024 + i * 256 + lane * 4) = w;
.LBB0_48:
	s_or_b64 exec, exec, s[0:1]
	v_lshrrev_b32_e32 v0, 6, v136
	v_and_b32_e32 v1, 63, v136
	s_lshl_b32 s8, s2, 3
	s_lshl_b32 s9, s94, 3
	v_readfirstlane_b32 s0, v0
	v_lshlrev_b32_e32 v2, 4, v1
	v_lshlrev_b32_e32 v3, 3, v1
	v_mbcnt_lo_u32_b32 v4, -1, 0
	s_add_i32 s8, s8, s0
	v_mbcnt_hi_u32_b32 v4, -1, v4
	v_cmp_eq_u32_e64 s[18:19], 0, v1
	v_xor_b32_e32 v16, 32, v4
	v_xor_b32_e32 v17, 16, v4
	v_xor_b32_e32 v18, 8, v4
	v_xor_b32_e32 v19, 4, v4
	v_xor_b32_e32 v20, 2, v4
	v_xor_b32_e32 v21, 1, v4
	v_lshlrev_b32_e32 v16, 2, v16
	v_lshlrev_b32_e32 v17, 2, v17
	v_lshlrev_b32_e32 v18, 2, v18
	v_lshlrev_b32_e32 v19, 2, v19
	v_lshlrev_b32_e32 v20, 2, v20
	v_lshlrev_b32_e32 v21, 2, v21
	v_mov_b32_e32 v22, 0x358637bd
	v_mov_b32_e32 v5, 0
	v_readlane_b32 s12, v250, 4
	v_readlane_b32 s13, v250, 5
	v_readlane_b32 s14, v250, 6
	v_readlane_b32 s15, v250, 7
	s_add_u32 s16, s44, 0x1a20000
	s_addc_u32 s17, s45, 0
	s_add_u32 s10, s44, 0x5e20000
	s_addc_u32 s11, s45, 0
	s_mov_b32 s27, 0x800000
	s_cmp_lt_i32 s8, 0x8800
	s_cbranch_scc0 .LBB0_55
	s_cmp_lt_i32 s8, 0x8000
	s_cselect_b32 s20, s12, s14
	s_cselect_b32 s21, s13, s15
	s_cselect_b32 s0, 0, 0x8000
	s_sub_i32 s0, s8, s0
	s_lshl_b32 s0, s0, 12
	s_add_u32 s20, s20, s0
	s_addc_u32 s21, s21, 0
	global_load_dwordx4 v[24:27], v2, s[20:21] nt
	global_load_dwordx4 v[28:31], v2, s[20:21] offset:1024 nt
	global_load_dwordx4 v[32:35], v2, s[20:21] offset:2048 nt
	global_load_dwordx4 v[36:39], v2, s[20:21] offset:3072 nt
	s_waitcnt vmcnt(0)
	s_branch .Lxcv_a_ready

; __device__ __forceinline__ unsigned cvt_pk_bf16(float lo, float hi) { unsigned r; asm volatile("v_cvt_pk_bf16_f32 %0, %1, %2" : "=v"(r) : "v"(lo), "v"(hi)); return r; }
; __device__ __forceinline__ void phase0(const Params& p) {
;     ...
;     for (int row = gw; row < T; row += nw) {
;         const float* xr = (row < T_P) ? p.in[0] + (size_t)row * 1024 : p.in[1] + (size_t)(row - T_P) * 1024;
;         float ss = 0.f;
; #pragma unroll
;         for (int i = 0; i < 4; ++i) {
;             const f32x4 v = *(const f32x4*)(xr + i * 256 + lane * 4);
;             ss += v[0] * v[0] + v[1] * v[1] + v[2] * v[2] + v[3] * v[3];
;             u32x2 w; w.x = cvt_pk_bf16(v[0], v[1]); w.y = cvt_pk_bf16(v[2], v[3]);
;             *(u32x2*)(xb + (size_t)row * 1024 + i * 256 + lane * 4) = w;
;         }
; #pragma unroll
;         for (int o = 32; o >= 1; o >>= 1) ss += __shfl_xor(ss, o);
;         if (lane == 0) rstd[row] = rsqrtf(ss * (1.f / 1024.f) + EPS);
;     }
.Lxcv_a_ready:
	s_add_i32 s26, s8, s9
	s_cmp_lt_i32 s26, 0x8800
	s_cbranch_scc0 .Lxcv_a_nopf
	s_cmp_lt_i32 s26, 0x8000
	s_cselect_b32 s20, s12, s14
	s_cselect_b32 s21, s13, s15
	s_cselect_b32 s0, 0, 0x8000
	s_sub_i32 s0, s26, s0
	s_lshl_b32 s0, s0, 12
	s_add_u32 s20, s20, s0
	s_addc_u32 s21, s21, 0
	global_load_dwordx4 v[50:53], v2, s[20:21] nt
	global_load_dwordx4 v[54:57], v2, s[20:21] offset:1024 nt
	global_load_dwordx4 v[58:61], v2, s[20:21] offset:2048 nt
	global_load_dwordx4 v[62:65], v2, s[20:21] offset:3072 nt
.Lxcv_a_nopf:
	s_lshl_b32 s0, s8, 11
	s_add_u32 s22, s16, s0
	s_addc_u32 s23, s17, 0
	v_cvt_pk_bf16_f32 v40, v24, v25
	v_cvt_pk_bf16_f32 v41, v26, v27
	v_cvt_pk_bf16_f32 v42, v28, v29
	v_cvt_pk_bf16_f32 v43, v30, v31
	v_cvt_pk_bf16_f32 v44, v32, v33
	v_cvt_pk_bf16_f32 v45, v34, v35
	v_cvt_pk_bf16_f32 v46, v36, v37
	v_cvt_pk_bf16_f32 v47, v38, v39
	global_store_dwordx2 v3, v[40:41], s[22:23]
	global_store_dwordx2 v3, v[42:43], s[22:23] offset:512
	global_store_dwordx2 v3, v[44:45], s[22:23] offset:1024
	global_store_dwordx2 v3, v[46:47], s[22:23] offset:1536
	v_mul_f32_e32 v12, v25, v25
	v_fmac_f32_e32 v12, v24, v24
	v_fmac_f32_e32 v12, v26, v26
	v_fmac_f32_e32 v12, v27, v27
	v_mul_f32_e32 v13, v29, v29
	v_fmac_f32_e32 v13, v28, v28
	v_fmac_f32_e32 v13, v30, v30
	v_fmac_f32_e32 v13, v31, v31
	v_add_f32_e32 v12, v12, v13
	v_mul_f32_e32 v13, v33, v33
	v_fmac_f32_e32 v13, v32, v32
	v_fmac_f32_e32 v13, v34, v34
	v_fmac_f32_e32 v13, v35, v35
	v_add_f32_e32 v12, v12, v13
	v_mul_f32_e32 v13, v37, v37
	v_fmac_f32_e32 v13, v36, v36
	v_fmac_f32_e32 v13, v38, v38
	v_fmac_f32_e32 v13, v39, v39
	v_add_f32_e32 v12, v12, v13
	ds_bpermute_b32 v13, v16, v12
	s_waitcnt lgkmcnt(0)
	v_add_f32_e32 v12, v12, v13
	ds_bpermute_b32 v13, v17, v12
	s_waitcnt lgkmcnt(0)
	v_add_f32_e32 v12, v12, v13
	ds_bpermute_b32 v13, v18, v12
	s_waitcnt lgkmcnt(0)
	v_add_f32_e32 v12, v12, v13
	ds_bpermute_b32 v13, v19, v12
	s_waitcnt lgkmcnt(0)
	v_add_f32_e32 v12, v12, v13
	ds_bpermute_b32 v13, v20, v12
	s_waitcnt lgkmcnt(0)
	v_add_f32_e32 v12, v12, v13
	ds_bpermute_b32 v13, v21, v12
	s_waitcnt lgkmcnt(0)
	v_add_f32_e32 v12, v12, v13
	v_fmamk_f32 v12, v12, 0x3a800000, v22
	v_mul_f32_e32 v13, 0x4b800000, v12
	v_cmp_gt_f32_e32 vcc, s27, v12
	s_lshl_b32 s0, s8, 2
	s_add_u32 s24, s10, s0
	v_cndmask_b32_e32 v12, v12, v13, vcc
	v_rsq_f32_e32 v12, v12
	s_addc_u32 s25, s11, 0
	v_mul_f32_e32 v13, 0x45800000, v12
	v_cndmask_b32_e32 v12, v12, v13, vcc
	s_mov_b64 exec, s[18:19]
	global_store_dword v5, v12, s[24:25]
	s_mov_b64 exec, -1
	s_mov_b32 s8, s26
	s_cmp_lt_i32 s8, 0x8800
	s_cbranch_scc0 .LBB0_55
	s_waitcnt vmcnt(5)
	s_add_i32 s26, s8, s9
	s_cmp_lt_i32 s26, 0x8800
	s_cbranch_scc0 .Lxcv_b_nopf
	s_cmp_lt_i32 s26, 0x8000
	s_cselect_b32 s20, s12, s14
	s_cselect_b32 s21, s13, s15
	s_cselect_b32 s0, 0, 0x8000
	s_sub_i32 s0, s26, s0
	s_lshl_b32 s0, s0, 12
	s_add_u32 s20, s20, s0
	s_addc_u32 s21, s21, 0
	global_load_dwordx4 v[24:27], v2, s[20:21] nt
	global_load_dwordx4 v[28:31], v2, s[20:21] offset:1024 nt
	global_load_dwordx4 v[32:35], v2, s[20:21] offset:2048 nt
	global_load_dwordx4 v[36:39], v2, s[20:21] offset:3072 nt
